# diff-attention P.V restructured k-step-major: exp/cvt of key slice j+1 interleaved between the four dv-block MFMAs of slice j (softmax VALU hidden under MFMA)
# speedup vs baseline: 1.0074x; 1.0074x over previous
; __device__ __forceinline__ unsigned cvtpk(float lo, float hi) { f32x2_t v = {lo, hi}; bf16x2_t b = __builtin_convertvector(v, bf16x2_t); return __builtin_bit_cast(unsigned, b); }
; #define ATT_MMAG(F, dvb) do { _Pragma("unroll") for (int j = 0; j < 4; ++j) o[dvb] = __builtin_amdgcn_mfma_f32_32x32x16_bf16(F[j], pb[j >> 1][j & 1], o[dvb], 0, 0, 0); } while (0)
; template <bool DIFF> ...
;     ...
;             const float d0 = c0 - m_run, d1 = c1 - m_run;
;             float rs0 = 0.f, rs1 = 0.f;
; #pragma unroll
;             for (int r = 0; r < 16; ++r) { s0[r] = __builtin_amdgcn_exp2f(__builtin_fmaf(s0[r], sc2, d0)); s1[r] = __builtin_amdgcn_exp2f(__builtin_fmaf(s1[r], sc2, d1)); rs0 += s0[r]; rs1 += s1[r]; }
;             l_run += rs0 + rs1;
;             bf16x8 pb[2][2];
; #pragma unroll
;             for (int g = 0; g < 2; ++g) {
;                 u32x4 w0, w1;
;                 w0.x = cvtpk(s0[8 * g], s0[8 * g + 1]); w0.y = cvtpk(s0[8 * g + 2], s0[8 * g + 3]); w0.z = cvtpk(s0[8 * g + 4], s0[8 * g + 5]); w0.w = cvtpk(s0[8 * g + 6], s0[8 * g + 7]);
;                 w1.x = cvtpk(s1[8 * g], s1[8 * g + 1]); w1.y = cvtpk(s1[8 * g + 2], s1[8 * g + 3]); w1.z = cvtpk(s1[8 * g + 4], s1[8 * g + 5]); w1.w = cvtpk(s1[8 * g + 6], s1[8 * g + 7]);
;                 pb[0][g] = __builtin_bit_cast(bf16x8, w0); pb[1][g] = __builtin_bit_cast(bf16x8, w1);
;             }
;             __builtin_amdgcn_sched_barrier(0);
;             ATT_MMAG(fa, 0); ATT_LOADG(fa, 2); __builtin_amdgcn_sched_barrier(0); ATT_MMAG(fb, 1); ATT_LOADG(fb, 3); __builtin_amdgcn_sched_barrier(0); ATT_MMAG(fa, 2); ATT_MMAG(fb, 3);
.LBB0_112:
	v_sub_f32_e32 v227, v213, v209
	v_sub_f32_e32 v226, v212, v209
	v_fmamk_f32 v98, v98, 0x3e38aa3b, v226
	v_fmamk_f32 v99, v99, 0x3e38aa3b, v226
	v_fmamk_f32 v100, v100, 0x3e38aa3b, v226
	v_fmamk_f32 v101, v101, 0x3e38aa3b, v226
	v_fmamk_f32 v102, v102, 0x3e38aa3b, v226
	v_fmamk_f32 v103, v103, 0x3e38aa3b, v226
	v_fmamk_f32 v104, v104, 0x3e38aa3b, v226
	v_fmamk_f32 v105, v105, 0x3e38aa3b, v226
	v_exp_f32_e32 v98, v98
	v_exp_f32_e32 v99, v99
	v_exp_f32_e32 v100, v100
	v_exp_f32_e32 v101, v101
	v_exp_f32_e32 v102, v102
	v_exp_f32_e32 v103, v103
	v_exp_f32_e32 v104, v104
	v_exp_f32_e32 v105, v105
	v_pk_add_f32 v[212:213], v[98:99], v[100:101]
	v_pk_add_f32 v[212:213], v[212:213], v[102:103]
	v_pk_add_f32 v[212:213], v[212:213], v[104:105]
	v_cvt_pk_bf16_f32 v98, v98, v99
	v_cvt_pk_bf16_f32 v99, v100, v101
	v_cvt_pk_bf16_f32 v100, v102, v103
	v_cvt_pk_bf16_f32 v101, v104, v105
	s_waitcnt lgkmcnt(8)
	s_nop 1
	v_mfma_f32_32x32x16_bf16 v[50:65], v[130:133], v[98:101], v[50:65]
	v_fmamk_f32 v106, v106, 0x3e38aa3b, v226
	v_fmamk_f32 v107, v107, 0x3e38aa3b, v226
	v_fmamk_f32 v108, v108, 0x3e38aa3b, v226
	v_fmamk_f32 v109, v109, 0x3e38aa3b, v226
	v_fmamk_f32 v110, v110, 0x3e38aa3b, v226
	v_fmamk_f32 v111, v111, 0x3e38aa3b, v226
	v_fmamk_f32 v112, v112, 0x3e38aa3b, v226
	v_mfma_f32_32x32x16_bf16 v[34:49], v[134:137], v[98:101], v[34:49]
	v_fmamk_f32 v113, v113, 0x3e38aa3b, v226
	v_exp_f32_e32 v106, v106
	v_exp_f32_e32 v107, v107
	v_exp_f32_e32 v108, v108
	v_exp_f32_e32 v109, v109
	v_exp_f32_e32 v110, v110
	v_exp_f32_e32 v111, v111
	v_mfma_f32_32x32x16_bf16 v[18:33], v[138:141], v[98:101], v[18:33]
	v_exp_f32_e32 v112, v112
	v_exp_f32_e32 v113, v113
	v_pk_add_f32 v[212:213], v[212:213], v[106:107]
	v_pk_add_f32 v[212:213], v[212:213], v[108:109]
	v_pk_add_f32 v[212:213], v[212:213], v[110:111]
	v_pk_add_f32 v[212:213], v[212:213], v[112:113]
	v_cvt_pk_bf16_f32 v106, v106, v107
	v_mfma_f32_32x32x16_bf16 v[2:17], v[142:145], v[98:101], v[2:17]
	ds_read_b64_tr_b16 v[130:131], v228 offset:24576
	ds_read_b64_tr_b16 v[132:133], v229 offset:26624
	ds_read_b64_tr_b16 v[134:135], v230 offset:24576
	ds_read_b64_tr_b16 v[136:137], v231 offset:26624
	ds_read_b64_tr_b16 v[138:139], v232 offset:24576
	ds_read_b64_tr_b16 v[140:141], v233 offset:26624
	ds_read_b64_tr_b16 v[142:143], v234 offset:24576
	ds_read_b64_tr_b16 v[144:145], v235 offset:26624
	v_cvt_pk_bf16_f32 v107, v108, v109
	v_cvt_pk_bf16_f32 v108, v110, v111
	v_cvt_pk_bf16_f32 v109, v112, v113
	s_waitcnt lgkmcnt(8)
	s_nop 1
	v_mfma_f32_32x32x16_bf16 v[50:65], v[146:149], v[106:109], v[50:65]
	v_fmamk_f32 v82, v82, 0x3e38aa3b, v227
	v_fmamk_f32 v83, v83, 0x3e38aa3b, v227
	v_fmamk_f32 v84, v84, 0x3e38aa3b, v227
	v_fmamk_f32 v85, v85, 0x3e38aa3b, v227
	v_fmamk_f32 v86, v86, 0x3e38aa3b, v227
	v_fmamk_f32 v87, v87, 0x3e38aa3b, v227
	v_fmamk_f32 v88, v88, 0x3e38aa3b, v227
	v_mfma_f32_32x32x16_bf16 v[34:49], v[150:153], v[106:109], v[34:49]
	v_fmamk_f32 v89, v89, 0x3e38aa3b, v227
	v_exp_f32_e32 v82, v82
	v_exp_f32_e32 v83, v83
	v_exp_f32_e32 v84, v84
	v_exp_f32_e32 v85, v85
	v_exp_f32_e32 v86, v86
	v_exp_f32_e32 v87, v87
	v_mfma_f32_32x32x16_bf16 v[18:33], v[154:157], v[106:109], v[18:33]
	v_exp_f32_e32 v88, v88
	v_exp_f32_e32 v89, v89
	v_pk_add_f32 v[212:213], v[212:213], v[82:83]
	v_pk_add_f32 v[212:213], v[212:213], v[84:85]
	v_pk_add_f32 v[212:213], v[212:213], v[86:87]
	v_pk_add_f32 v[212:213], v[212:213], v[88:89]
	v_cvt_pk_bf16_f32 v82, v82, v83
	v_mfma_f32_32x32x16_bf16 v[2:17], v[158:161], v[106:109], v[2:17]
	ds_read_b64_tr_b16 v[146:147], v228 offset:28672
	ds_read_b64_tr_b16 v[148:149], v229 offset:30720
	ds_read_b64_tr_b16 v[150:151], v230 offset:28672
	ds_read_b64_tr_b16 v[152:153], v231 offset:30720
	ds_read_b64_tr_b16 v[154:155], v232 offset:28672
	ds_read_b64_tr_b16 v[156:157], v233 offset:30720
	ds_read_b64_tr_b16 v[158:159], v234 offset:28672
	ds_read_b64_tr_b16 v[160:161], v235 offset:30720
	v_cvt_pk_bf16_f32 v83, v84, v85
	v_cvt_pk_bf16_f32 v84, v86, v87
	v_cvt_pk_bf16_f32 v85, v88, v89
	s_waitcnt lgkmcnt(8)
	s_nop 1
	v_mfma_f32_32x32x16_bf16 v[50:65], v[130:133], v[82:85], v[50:65]
	v_fmamk_f32 v90, v90, 0x3e38aa3b, v227
	v_fmamk_f32 v91, v91, 0x3e38aa3b, v227
	v_fmamk_f32 v92, v92, 0x3e38aa3b, v227
	v_fmamk_f32 v93, v93, 0x3e38aa3b, v227
	v_fmamk_f32 v94, v94, 0x3e38aa3b, v227
	v_fmamk_f32 v95, v95, 0x3e38aa3b, v227
	v_fmamk_f32 v96, v96, 0x3e38aa3b, v227
	v_mfma_f32_32x32x16_bf16 v[34:49], v[134:137], v[82:85], v[34:49]
	v_fmamk_f32 v97, v97, 0x3e38aa3b, v227
	v_exp_f32_e32 v90, v90
	v_exp_f32_e32 v91, v91
	v_exp_f32_e32 v92, v92
	v_exp_f32_e32 v93, v93
	v_exp_f32_e32 v94, v94
	v_exp_f32_e32 v95, v95
	v_mfma_f32_32x32x16_bf16 v[18:33], v[138:141], v[82:85], v[18:33]
	v_exp_f32_e32 v96, v96
	v_exp_f32_e32 v97, v97
	v_pk_add_f32 v[212:213], v[212:213], v[90:91]
	v_pk_add_f32 v[212:213], v[212:213], v[92:93]
	v_pk_add_f32 v[212:213], v[212:213], v[94:95]
	v_pk_add_f32 v[212:213], v[212:213], v[96:97]
	v_cvt_pk_bf16_f32 v90, v90, v91
	v_mfma_f32_32x32x16_bf16 v[2:17], v[142:145], v[82:85], v[2:17]
	v_cvt_pk_bf16_f32 v91, v92, v93
	v_cvt_pk_bf16_f32 v92, v94, v95
	v_cvt_pk_bf16_f32 v93, v96, v97
	s_waitcnt lgkmcnt(0)
	s_nop 1
	v_mfma_f32_32x32x16_bf16 v[50:65], v[146:149], v[90:93], v[50:65]
	v_mfma_f32_32x32x16_bf16 v[34:49], v[150:153], v[90:93], v[34:49]
	v_mfma_f32_32x32x16_bf16 v[18:33], v[154:157], v[90:93], v[18:33]
	v_mfma_f32_32x32x16_bf16 v[2:17], v[158:161], v[90:93], v[2:17]
	v_add_f32_e32 v212, v212, v213
	s_nop 0
	v_add_f32_e32 v205, v205, v212

; #define LAS __attribute__((address_space(3)))
; template <bool DIFF> ...
;     ...
;                 c0 = sl2 * (float)(64 * kt - wrow); c1 = sl2 * (float)(64 * kt + 32 - wrow);
;                 if (64 * kt + 64 > wrow) {
;                     asm volatile("" ::: "memory");
;                     const int irel = wrow + l32 - 64 * kt - hi * 4;
; #pragma unroll
;                     for (int r = 0; r < 16; ++r) { const int cr = (r >> 2) * 8 + (r & 3); if (cr > irel) s0[r] = -INFINITY; if (cr + 32 > irel) s1[r] = -INFINITY; }
;                 }
;             }
;             LAS const unsigned char* va = vb + (hi * 4 + ((lane & 15) >> 2)) * VSTR + (DIFF ? 0 : c * 256) + (((lane >> 4) & 1) * 16 + 4 * (lane & 3)) * 2;
;             bf16x8 fa[4], fb[4];
;             const int vq = (lane & 15) >> 2, vp = lane & 3, vg1 = (lane >> 4) & 1;
;             const int vs0 = 256 * (hi * 4 + vq) + 16 * ((2 * vg1 + (vp >> 1)) ^ hi) + 8 * (vp & 1), vs1 = 256 * (hi * 4 + 8 + vq) + 16 * ((2 * vg1 + (vp >> 1)) ^ (hi + 2)) + 8 * (vp & 1);
;     ...
;             float mx0 = s0[0], mx1 = s1[0];
; #pragma unroll
;             for (int r = 1; r < 16; r += 2) { mx0 = fmaxf(fmaxf(mx0, s0[r]), s0[r + 1 < 16 ? r + 1 : r]); mx1 = fmaxf(fmaxf(mx1, s1[r]), s1[r + 1 < 16 ? r + 1 : r]); }
;             float mx = fmaxf(__builtin_fmaf(mx0, sc2, c0), __builtin_fmaf(mx1, sc2, c1));
;             mx = fmaxf(mx, __shfl_xor(mx, 32));
;             __builtin_amdgcn_sched_barrier(0);
;             ATT_LOADG(fa, 0); ATT_LOADG(fb, 1);
;             __builtin_amdgcn_sched_barrier(0);
;             if (__builtin_amdgcn_ballot_w64(mx > m_run) != 0ull) {
;                 const float mnew = fmaxf(m_run, mx), alpha = __builtin_amdgcn_exp2f(m_run - mnew); m_run = mnew; l_run *= alpha;
; #pragma unroll
;                 for (int i = 0; i < 4; ++i)
; #pragma unroll
;                     for (int r = 0; r < 16; ++r) o[i][r] *= alpha;
;             }
.LBB0_119:
	s_add_i32 s0, s24, s22
	s_add_i32 s1, s0, 64
	s_addk_i32 s0, 0x60
	v_cvt_f32_i32_e32 v130, s1
	v_cvt_f32_i32_e32 v131, s0
	s_nop 5
	v_max_f32_e32 v132, v82, v82
	v_mul_f32_e32 v212, v182, v130
	v_mul_f32_e32 v213, v182, v131
	v_max_f32_e32 v130, v99, v99
	v_max_f32_e32 v131, v98, v98
	v_max_f32_e32 v130, v131, v130
	v_max_f32_e32 v131, v83, v83
	v_max_f32_e32 v131, v132, v131
	v_max3_f32 v130, v130, v100, v101
	v_max3_f32 v131, v131, v84, v85
	v_max3_f32 v130, v130, v102, v103
	v_max3_f32 v131, v131, v86, v87
	v_max3_f32 v130, v130, v104, v105
	v_max3_f32 v131, v131, v88, v89
	v_max3_f32 v130, v130, v106, v107
	v_max3_f32 v131, v131, v90, v91
	v_max3_f32 v130, v130, v108, v109
	v_max3_f32 v131, v131, v92, v93
	v_max3_f32 v130, v130, v110, v111
	v_max3_f32 v131, v131, v94, v95
	v_max3_f32 v130, v130, v112, v113
	v_max3_f32 v131, v131, v96, v97
	v_fmamk_f32 v130, v130, 0x3e38aa3b, v212
	v_fmamk_f32 v131, v131, 0x3e38aa3b, v213
	v_max_f32_e32 v214, v130, v131
	ds_bpermute_b32 v215, v170, v214
	v_add_u32_e32 v130, s23, v186
	v_add_u32_e32 v131, s23, v198
	v_add3_u32 v210, v130, v163, v197
	v_add3_u32 v211, v131, v163, v197
	v_add_u32_e32 v228, v210, v199
	v_add_u32_e32 v229, v211, v199
	v_add_u32_e32 v230, v210, v206
	v_add_u32_e32 v231, v211, v206
	v_add_u32_e32 v232, v210, v207
	v_add_u32_e32 v233, v211, v207
	v_add_u32_e32 v234, v210, v208
	v_add_u32_e32 v235, v211, v208
	ds_read_b64_tr_b16 v[130:131], v228 offset:16384
	ds_read_b64_tr_b16 v[132:133], v229 offset:18432
	ds_read_b64_tr_b16 v[134:135], v230 offset:16384
	ds_read_b64_tr_b16 v[136:137], v231 offset:18432
	ds_read_b64_tr_b16 v[138:139], v232 offset:16384
	ds_read_b64_tr_b16 v[140:141], v233 offset:18432
	ds_read_b64_tr_b16 v[142:143], v234 offset:16384
	ds_read_b64_tr_b16 v[144:145], v235 offset:18432
	ds_read_b64_tr_b16 v[146:147], v228 offset:20480
	ds_read_b64_tr_b16 v[148:149], v229 offset:22528
	ds_read_b64_tr_b16 v[150:151], v230 offset:20480
	ds_read_b64_tr_b16 v[152:153], v231 offset:22528
	ds_read_b64_tr_b16 v[154:155], v232 offset:20480
	ds_read_b64_tr_b16 v[156:157], v233 offset:22528
	ds_read_b64_tr_b16 v[158:159], v234 offset:20480
	ds_read_b64_tr_b16 v[160:161], v235 offset:22528
	s_waitcnt lgkmcnt(15)
	v_max_f32_e32 v215, v215, v215
	v_max_f32_e32 v214, v214, v215
	v_cmp_gt_f32_e32 vcc, v214, v209
	s_cbranch_vccz .LBB0_112
	v_max_f32_e32 v214, v214, v214
	v_max_f32_e32 v215, v209, v209
	v_max_f32_e32 v215, v215, v214
	v_sub_f32_e32 v209, v209, v215
	v_exp_f32_e32 v214, v209
	v_mov_b32_e32 v209, v215
	v_pk_mul_f32 v[64:65], v[64:65], v[214:215] op_sel_hi:[1,0]
	v_pk_mul_f32 v[62:63], v[62:63], v[214:215] op_sel_hi:[1,0]
	v_pk_mul_f32 v[60:61], v[60:61], v[214:215] op_sel_hi:[1,0]
	v_pk_mul_f32 v[58:59], v[58:59], v[214:215] op_sel_hi:[1,0]
	v_pk_mul_f32 v[56:57], v[56:57], v[214:215] op_sel_hi:[1,0]
	v_pk_mul_f32 v[54:55], v[54:55], v[214:215] op_sel_hi:[1,0]
	v_pk_mul_f32 v[52:53], v[52:53], v[214:215] op_sel_hi:[1,0]
	v_pk_mul_f32 v[50:51], v[50:51], v[214:215] op_sel_hi:[1,0]
	v_pk_mul_f32 v[48:49], v[48:49], v[214:215] op_sel_hi:[1,0]
	v_pk_mul_f32 v[46:47], v[46:47], v[214:215] op_sel_hi:[1,0]
	v_pk_mul_f32 v[44:45], v[44:45], v[214:215] op_sel_hi:[1,0]
	v_pk_mul_f32 v[42:43], v[42:43], v[214:215] op_sel_hi:[1,0]
	v_pk_mul_f32 v[40:41], v[40:41], v[214:215] op_sel_hi:[1,0]
	v_pk_mul_f32 v[38:39], v[38:39], v[214:215] op_sel_hi:[1,0]
	v_pk_mul_f32 v[36:37], v[36:37], v[214:215] op_sel_hi:[1,0]
	v_pk_mul_f32 v[34:35], v[34:35], v[214:215] op_sel_hi:[1,0]
	v_pk_mul_f32 v[32:33], v[32:33], v[214:215] op_sel_hi:[1,0]
	v_pk_mul_f32 v[30:31], v[30:31], v[214:215] op_sel_hi:[1,0]
	v_pk_mul_f32 v[28:29], v[28:29], v[214:215] op_sel_hi:[1,0]
	v_pk_mul_f32 v[26:27], v[26:27], v[214:215] op_sel_hi:[1,0]
	v_pk_mul_f32 v[24:25], v[24:25], v[214:215] op_sel_hi:[1,0]
	v_pk_mul_f32 v[22:23], v[22:23], v[214:215] op_sel_hi:[1,0]
	v_pk_mul_f32 v[20:21], v[20:21], v[214:215] op_sel_hi:[1,0]
	v_pk_mul_f32 v[18:19], v[18:19], v[214:215] op_sel_hi:[1,0]
	v_pk_mul_f32 v[16:17], v[16:17], v[214:215] op_sel_hi:[1,0]
	v_pk_mul_f32 v[14:15], v[14:15], v[214:215] op_sel_hi:[1,0]
	v_pk_mul_f32 v[12:13], v[12:13], v[214:215] op_sel_hi:[1,0]
	v_pk_mul_f32 v[10:11], v[10:11], v[214:215] op_sel_hi:[1,0]
	v_pk_mul_f32 v[8:9], v[8:9], v[214:215] op_sel_hi:[1,0]
	v_pk_mul_f32 v[6:7], v[6:7], v[214:215] op_sel_hi:[1,0]
	v_pk_mul_f32 v[4:5], v[4:5], v[214:215] op_sel_hi:[1,0]
	v_pk_mul_f32 v[2:3], v[2:3], v[214:215] op_sel_hi:[1,0]
	v_mul_f32_e32 v205, v205, v214
	s_branch .LBB0_112
